# attention key loops: one static s_setprio 1 for waves 4-7 (the second-dispatched half) for the duration of the unit loop
# speedup vs baseline: 1.0090x; 1.0090x over previous
; #define LAS __attribute__((address_space(3)))
; #define GAS __attribute__((address_space(1)))
; #define AT_LOAD(t) do { const GAS u32x4* Kg_ = (const GAS u32x4*)(Kp + (size_t)(t) * 128 * DK); const GAS u32x4* Vg_ = (const GAS u32x4*)(Vp + (size_t)(t) * 128 * 64); \
;         _Pragma("unroll") for (int i_ = 0; i_ < NKC; ++i_) kreg[i_] = Kg_[tid + 512 * i_]; vreg[0] = Vg_[tid]; vreg[1] = Vg_[tid + 512]; } while (0)
; #define AT_STORE(bf_) do { LAS unsigned char* nb_ = lds + (bf_) * AT_KBUF; _Pragma("unroll") for (int i_ = 0; i_ < NKC; ++i_) *(LAS u32x4*)(nb_ + koff[i_]) = kreg[i_]; \
;         *(LAS u32x4*)(lds + (bf_) * AT_VBUF + voff[0]) = vreg[0]; *(LAS u32x4*)(lds + (bf_) * AT_VBUF + voff[1]) = vreg[1]; } while (0)
; template <int DK>
; __device__ __forceinline__ void attn_unit(LAS unsigned char* lds, const GAS bf16* Qp, const GAS bf16* Kp, const GAS bf16* Vp, GAS bf16* Yp, int b, int j, int nkeys, int tid, int lane, int wave) {
;     ...
;     { const GAS bf16* Qw = Qp + (size_t)(256 * j + wave * 32 + r32) * DK + hi * 8;
; #pragma unroll
;       for (int d0 = 0; d0 < ND; ++d0) qr[d0] = *(const GAS bf16x8*)(Qw + d0 * 16); }
;     int koff[NKC], voff[2];
; #pragma unroll
;     for (int i = 0; i < NKC; ++i) { const int kc = tid + 512 * i; koff[i] = (kc / CPR) * KSTR + (kc % CPR) * 16; }
; #pragma unroll
;     for (int i = 0; i < 2; ++i) { const int vc = tid + 512 * i, vrow = vc >> 3, vch = vc & 7; voff[i] = AT_VOFF + (vch >> 2) * 8192 + (vrow >> 4) * 1024 + (vrow & 15) * 64 + (vch & 3) * 16; }
;     const int NT = nkeys >> 7;
;     u32x4 kreg[NKC], vreg[2];
;     ...
;     AT_LOAD(0); AT_STORE(0);
;     if (NT > 1) AT_LOAD(1);
;     __syncthreads();
;     LAS float* wsf = (LAS float*)(lds + AT_WSF) + wave * 32;
;     float mhat = 0.f;
;     f32x16 o0, o1, ol, negm;
; #pragma unroll
;     for (int r = 0; r < 16; ++r) { o0[r] = 0.f; o1[r] = 0.f; ol[r] = 0.f; negm[r] = 0.f; }
;     const bf16x8 ones = {0x3F80, 0x3F80, 0x3F80, 0x3F80, 0x3F80, 0x3F80, 0x3F80, 0x3F80};
;     const int kfo = r32 * KSTR + hi * 16;
;     const int vfo = AT_VOFF + (4 * hi + ((lane & 15) >> 2)) * 64 + ((lane >> 4) & 1) * 32 + (lane & 3) * 8;
.LBB0_132:
	s_andn2_b64 vcc, exec, s[22:23]
	s_cbranch_vccnz .LBB0_168
	s_mul_hi_i32 s73, s37, 0x2aaaaaab
	s_lshr_b32 s4, s73, 31
	s_add_i32 s73, s73, s4
	s_mul_i32 s4, s73, 6
	s_sub_i32 s74, s37, s4
	s_cmp_lg_u32 s24, 0
	s_cselect_b64 s[22:23], -1, 0
	s_cmp_eq_u32 s24, 0
	s_cselect_b64 s[44:45], -1, 0
	s_and_b64 s[4:5], s[44:45], exec
	s_movk_i32 s4, 0x100
	v_cmp_eq_u32_e32 vcc, 0, v0
	s_cselect_b32 s4, s4, 0x900
	s_mul_hi_i32 s5, s37, 0x48000
	s_mul_i32 s6, s37, 0x48000
	s_cbranch_vccnz .LBB0_151
	s_mul_i32 s10, s37, 0x6c000
	s_mul_hi_i32 s7, s37, 0x6c000
	s_add_u32 s8, s58, s10
	s_addc_u32 s9, s59, s7
	s_add_u32 s46, s60, s10
	s_addc_u32 s47, s61, s7
	s_add_u32 s48, s64, s6
	s_addc_u32 s49, s65, s5
	s_lshl_b32 s7, s24, 8
	v_readlane_b32 s10, v254, 2
	s_add_i32 s7, s7, s10
	v_or_b32_e32 v0, s7, v231
	v_mov_b64_e32 v[2:3], s[8:9]
	v_mad_i64_i32 v[2:3], s[8:9], v0, s76, v[2:3]
	v_lshl_add_u64 v[4:5], s[46:47], 0, v[206:207]
	s_movk_i32 s8, 0x2000
	v_add_co_u32_e32 v6, vcc, s8, v4
	v_lshl_add_u64 v[2:3], v[200:201], 1, v[2:3]
	s_nop 0
	v_addc_co_u32_e32 v7, vcc, 0, v5, vcc
	s_movk_i32 s9, 0x4000
	global_load_dwordx4 v[144:147], v[2:3], off
	global_load_dwordx4 v[148:151], v[2:3], off offset:32
	global_load_dwordx4 v[152:155], v[2:3], off offset:64
	global_load_dwordx4 v[156:159], v[2:3], off offset:96
	global_load_dwordx4 v[12:15], v[4:5], off
	global_load_dwordx4 v[16:19], v[6:7], off
	v_add_co_u32_e32 v6, vcc, s9, v4
	v_lshl_add_u64 v[8:9], s[48:49], 0, v[206:207]
	s_nop 0
	v_addc_co_u32_e32 v7, vcc, 0, v5, vcc
	global_load_dwordx4 v[20:23], v[6:7], off
	global_load_dwordx4 v[24:27], v[8:9], off
	v_add_co_u32_e32 v6, vcc, s8, v8
	s_movk_i32 s10, 0x6000
	s_nop 0
	v_addc_co_u32_e32 v7, vcc, 0, v9, vcc
	global_load_dwordx4 v[28:31], v[6:7], off
	v_add_co_u32_e32 v6, vcc, s10, v4
	s_mov_b32 s8, 0x8000
	s_nop 0
	v_addc_co_u32_e32 v7, vcc, 0, v5, vcc
	global_load_dwordx4 v[160:163], v[6:7], off
	v_add_co_u32_e32 v6, vcc, s8, v4
	s_mov_b32 s8, 0xa000
	s_nop 0
	v_addc_co_u32_e32 v7, vcc, 0, v5, vcc
	v_add_co_u32_e32 v4, vcc, s8, v4
	v_add_u32_e32 v32, 0, v234
	s_nop 0
	v_addc_co_u32_e32 v5, vcc, 0, v5, vcc
	global_load_dwordx4 v[164:167], v[6:7], off
	global_load_dwordx4 v[176:179], v[4:5], off
	v_add_co_u32_e32 v4, vcc, s9, v8
	v_mov_b32_e32 v0, v1
	s_nop 0
	v_addc_co_u32_e32 v5, vcc, 0, v9, vcc
	v_add_co_u32_e32 v6, vcc, s10, v8
	v_mov_b32_e32 v8, v1
	s_nop 0
	v_addc_co_u32_e32 v7, vcc, 0, v9, vcc
	global_load_dwordx4 v[180:183], v[4:5], off
	global_load_dwordx4 v[184:187], v[6:7], off
	global_load_dwordx4 v[168:171], v[2:3], off offset:128
	global_load_dwordx4 v[172:175], v[2:3], off offset:160
	v_mov_b32_e32 v2, v1
	v_mov_b32_e32 v3, v1
	v_mov_b32_e32 v4, v1
	v_mov_b32_e32 v5, v1
	v_mov_b32_e32 v6, v1
	v_mov_b32_e32 v7, v1
	v_mov_b32_e32 v9, v1
	v_mov_b32_e32 v10, v1
	v_mov_b32_e32 v11, v1
	s_lshr_b32 s8, s4, 7
	v_mov_b32_e32 v248, 0
	s_sub_i32 s9, 0, s8
	s_mov_b32 s10, 2
	v_mov_b32_e32 v64, 0
	v_mov_b32_e32 v65, v248
	v_mov_b32_e32 v66, v248
	v_mov_b32_e32 v67, v248
	v_mov_b32_e32 v68, v248
	v_mov_b32_e32 v69, v248
	v_mov_b32_e32 v70, v248
	v_mov_b32_e32 v71, v248
	v_mov_b32_e32 v72, v248
	v_mov_b32_e32 v73, v248
	v_mov_b32_e32 v74, v248
	v_mov_b32_e32 v75, v248
	v_mov_b32_e32 v76, v248
	v_mov_b32_e32 v77, v248
	v_mov_b32_e32 v78, v248
	v_mov_b32_e32 v79, v248
	s_waitcnt vmcnt(11)
	ds_write_b128 v246, v[12:15]
	s_waitcnt vmcnt(10)
	ds_write_b128 v247, v[16:19]
	s_waitcnt vmcnt(9)
	ds_write_b128 v32, v[20:23]
	s_waitcnt vmcnt(8)
	ds_write_b128 v245, v[24:27] offset:53248
	s_waitcnt vmcnt(7)
	ds_write_b128 v245, v[28:31] offset:57344
	v_mov_b32_e32 v14, v1
	v_mov_b32_e32 v15, v1
	v_mov_b32_e32 v12, v1
	v_mov_b32_e32 v13, v1
	v_mov_b64_e32 v[46:47], v[14:15]
	v_mov_b64_e32 v[30:31], v[14:15]
	v_mov_b64_e32 v[62:63], v[14:15]
	v_mov_b64_e32 v[44:45], v[12:13]
	v_mov_b64_e32 v[42:43], v[10:11]
	v_mov_b64_e32 v[40:41], v[8:9]
	v_mov_b64_e32 v[38:39], v[6:7]
	v_mov_b64_e32 v[36:37], v[4:5]
	v_mov_b64_e32 v[34:35], v[2:3]
	v_mov_b64_e32 v[32:33], v[0:1]
	v_mov_b64_e32 v[28:29], v[12:13]
	v_mov_b64_e32 v[26:27], v[10:11]
	v_mov_b64_e32 v[24:25], v[8:9]
	v_mov_b64_e32 v[22:23], v[6:7]
	v_mov_b64_e32 v[20:21], v[4:5]
	v_mov_b64_e32 v[18:19], v[2:3]
	v_mov_b64_e32 v[16:17], v[0:1]
	v_mov_b64_e32 v[60:61], v[12:13]
	v_mov_b64_e32 v[58:59], v[10:11]
	v_mov_b64_e32 v[56:57], v[8:9]
	v_mov_b64_e32 v[54:55], v[6:7]
	v_mov_b64_e32 v[52:53], v[4:5]
	v_mov_b64_e32 v[50:51], v[2:3]
	v_mov_b64_e32 v[48:49], v[0:1]
	s_waitcnt lgkmcnt(0)
	s_barrier
	s_cmp_lt_u32 s97, 4
	s_cbranch_scc1 .Lprio_1
	s_setprio 1
; __device__ __forceinline__ int crow(int r, int hi) { return (r & 3) + 8 * (r >> 2) + 4 * hi; }
; template <int DK>
; __device__ __forceinline__ void attn_unit(LAS unsigned char* lds, const GAS bf16* Qp, const GAS bf16* Kp, const GAS bf16* Vp, GAS bf16* Yp, int b, int j, int nkeys, int tid, int lane, int wave) {
;     ...
;         if (t == 0 || __any(rm > 8.0f)) {
;             const float dl = (t == 0) ? rm : fmaxf(rm, 0.f), f = __builtin_amdgcn_exp2f(-dl);
;             mhat += dl;
; #pragma unroll
;             for (int r = 0; r < 16; ++r) { p[0][r] -= dl; p[1][r] -= dl; p[2][r] -= dl; p[3][r] -= dl; negm[r] = -mhat; }
;             if (hi == 0) wsf[r32] = f;
;             asm volatile("s_waitcnt lgkmcnt(0)" ::: "memory");
; #pragma unroll
;             for (int r = 0; r < 16; ++r) { const float fr = wsf[crow(r, hi)]; o0[r] *= fr; o1[r] *= fr; ol[r] *= fr; }
;             asm volatile("s_waitcnt lgkmcnt(0)" ::: "memory");
.Lprio_1:
	s_branch .LBB0_137
.LBB0_135:
	s_or_b64 exec, exec, s[50:51]
	v_add_f32_e32 v248, v248, v0
	v_pk_add_f32 v[128:129], v[128:129], v[0:1] op_sel_hi:[1,0] neg_lo:[0,1] neg_hi:[0,1]
	v_pk_add_f32 v[112:113], v[112:113], v[0:1] op_sel_hi:[1,0] neg_lo:[0,1] neg_hi:[0,1]
	v_pk_add_f32 v[96:97], v[96:97], v[0:1] op_sel_hi:[1,0] neg_lo:[0,1] neg_hi:[0,1]
	v_pk_add_f32 v[80:81], v[80:81], v[0:1] op_sel_hi:[1,0] neg_lo:[0,1] neg_hi:[0,1]
	v_pk_add_f32 v[130:131], v[130:131], v[0:1] op_sel_hi:[1,0] neg_lo:[0,1] neg_hi:[0,1]
	v_pk_add_f32 v[114:115], v[114:115], v[0:1] op_sel_hi:[1,0] neg_lo:[0,1] neg_hi:[0,1]
	v_pk_add_f32 v[98:99], v[98:99], v[0:1] op_sel_hi:[1,0] neg_lo:[0,1] neg_hi:[0,1]
	v_pk_add_f32 v[82:83], v[82:83], v[0:1] op_sel_hi:[1,0] neg_lo:[0,1] neg_hi:[0,1]
	v_pk_add_f32 v[132:133], v[132:133], v[0:1] op_sel_hi:[1,0] neg_lo:[0,1] neg_hi:[0,1]
	v_pk_add_f32 v[116:117], v[116:117], v[0:1] op_sel_hi:[1,0] neg_lo:[0,1] neg_hi:[0,1]
	v_pk_add_f32 v[100:101], v[100:101], v[0:1] op_sel_hi:[1,0] neg_lo:[0,1] neg_hi:[0,1]
	v_pk_add_f32 v[84:85], v[84:85], v[0:1] op_sel_hi:[1,0] neg_lo:[0,1] neg_hi:[0,1]
	v_pk_add_f32 v[134:135], v[134:135], v[0:1] op_sel_hi:[1,0] neg_lo:[0,1] neg_hi:[0,1]
	v_pk_add_f32 v[118:119], v[118:119], v[0:1] op_sel_hi:[1,0] neg_lo:[0,1] neg_hi:[0,1]
	v_pk_add_f32 v[102:103], v[102:103], v[0:1] op_sel_hi:[1,0] neg_lo:[0,1] neg_hi:[0,1]
	v_pk_add_f32 v[86:87], v[86:87], v[0:1] op_sel_hi:[1,0] neg_lo:[0,1] neg_hi:[0,1]
	v_pk_add_f32 v[136:137], v[136:137], v[0:1] op_sel_hi:[1,0] neg_lo:[0,1] neg_hi:[0,1]
	v_pk_add_f32 v[120:121], v[120:121], v[0:1] op_sel_hi:[1,0] neg_lo:[0,1] neg_hi:[0,1]
	v_pk_add_f32 v[104:105], v[104:105], v[0:1] op_sel_hi:[1,0] neg_lo:[0,1] neg_hi:[0,1]
	v_pk_add_f32 v[88:89], v[88:89], v[0:1] op_sel_hi:[1,0] neg_lo:[0,1] neg_hi:[0,1]
	v_pk_add_f32 v[138:139], v[138:139], v[0:1] op_sel_hi:[1,0] neg_lo:[0,1] neg_hi:[0,1]
	v_pk_add_f32 v[122:123], v[122:123], v[0:1] op_sel_hi:[1,0] neg_lo:[0,1] neg_hi:[0,1]
	v_pk_add_f32 v[106:107], v[106:107], v[0:1] op_sel_hi:[1,0] neg_lo:[0,1] neg_hi:[0,1]
	v_pk_add_f32 v[90:91], v[90:91], v[0:1] op_sel_hi:[1,0] neg_lo:[0,1] neg_hi:[0,1]
	v_pk_add_f32 v[140:141], v[140:141], v[0:1] op_sel_hi:[1,0] neg_lo:[0,1] neg_hi:[0,1]
	v_pk_add_f32 v[124:125], v[124:125], v[0:1] op_sel_hi:[1,0] neg_lo:[0,1] neg_hi:[0,1]
	v_pk_add_f32 v[108:109], v[108:109], v[0:1] op_sel_hi:[1,0] neg_lo:[0,1] neg_hi:[0,1]
	v_pk_add_f32 v[92:93], v[92:93], v[0:1] op_sel_hi:[1,0] neg_lo:[0,1] neg_hi:[0,1]
	v_pk_add_f32 v[142:143], v[142:143], v[0:1] op_sel_hi:[1,0] neg_lo:[0,1] neg_hi:[0,1]
	v_pk_add_f32 v[126:127], v[126:127], v[0:1] op_sel_hi:[1,0] neg_lo:[0,1] neg_hi:[0,1]
	v_pk_add_f32 v[110:111], v[110:111], v[0:1] op_sel_hi:[1,0] neg_lo:[0,1] neg_hi:[0,1]
	v_pk_add_f32 v[94:95], v[94:95], v[0:1] op_sel_hi:[1,0] neg_lo:[0,1] neg_hi:[0,1]
	s_waitcnt lgkmcnt(0)
	v_add_u32_e32 v0, s63, v236
	ds_read_b128 v[2:5], v0
	ds_read_b128 v[6:9], v0 offset:32
	ds_read_b128 v[10:13], v0 offset:64
	ds_read_b128 v[64:67], v0 offset:96
	s_waitcnt lgkmcnt(0)
	v_xor_b32_e32 v79, 0x80000000, v248
	s_waitcnt lgkmcnt(2)
	v_pk_mul_f32 v[36:37], v[36:37], v[6:7]
	s_waitcnt lgkmcnt(1)
	v_pk_mul_f32 v[40:41], v[40:41], v[10:11]
	s_waitcnt lgkmcnt(0)
	v_pk_mul_f32 v[44:45], v[44:45], v[64:65]
	v_pk_mul_f32 v[46:47], v[46:47], v[66:67]
	v_pk_mul_f32 v[42:43], v[42:43], v[12:13]
	v_pk_mul_f32 v[38:39], v[38:39], v[8:9]
	v_pk_mul_f32 v[34:35], v[34:35], v[4:5]
	v_pk_mul_f32 v[32:33], v[32:33], v[2:3]
	v_pk_mul_f32 v[28:29], v[28:29], v[64:65]
	v_pk_mul_f32 v[24:25], v[24:25], v[10:11]
	v_pk_mul_f32 v[20:21], v[20:21], v[6:7]
	v_pk_mul_f32 v[30:31], v[30:31], v[66:67]
	v_pk_mul_f32 v[26:27], v[26:27], v[12:13]
	v_pk_mul_f32 v[22:23], v[22:23], v[8:9]
	v_pk_mul_f32 v[18:19], v[18:19], v[4:5]
	v_pk_mul_f32 v[16:17], v[16:17], v[2:3]
	v_pk_mul_f32 v[60:61], v[60:61], v[64:65]
	v_pk_mul_f32 v[56:57], v[56:57], v[10:11]
	v_pk_mul_f32 v[52:53], v[52:53], v[6:7]
	v_pk_mul_f32 v[62:63], v[62:63], v[66:67]
	v_pk_mul_f32 v[58:59], v[58:59], v[12:13]
	v_pk_mul_f32 v[54:55], v[54:55], v[8:9]
	v_pk_mul_f32 v[50:51], v[50:51], v[4:5]
	v_pk_mul_f32 v[48:49], v[48:49], v[2:3]
	v_mov_b32_e32 v78, v79
	v_mov_b32_e32 v77, v79
	v_mov_b32_e32 v76, v79
	v_mov_b32_e32 v75, v79
	v_mov_b32_e32 v74, v79
	v_mov_b32_e32 v73, v79
	v_mov_b32_e32 v72, v79
	v_mov_b32_e32 v71, v79
	v_mov_b32_e32 v70, v79
	v_mov_b32_e32 v69, v79
	v_mov_b32_e32 v68, v79
	v_mov_b32_e32 v67, v79
	v_mov_b32_e32 v66, v79
	v_mov_b32_e32 v65, v79
	v_mov_b32_e32 v64, v79

; #define GAS __attribute__((address_space(1)))
; __device__ __forceinline__ unsigned f2bf(float f) { unsigned u = __builtin_bit_cast(unsigned, f); return (u + 0x7fffu + ((u >> 16) & 1u)) >> 16; }
; __device__ __forceinline__ int crow(int r, int hi) { return (r & 3) + 8 * (r >> 2) + 4 * hi; }
; template <int DK>
; __device__ __forceinline__ void attn_unit(LAS unsigned char* lds, const GAS bf16* Qp, const GAS bf16* Kp, const GAS bf16* Vp, GAS bf16* Yp, int b, int j, int nkeys, int tid, int lane, int wave) {
;     ...
;     const int pos0 = 256 * j + wave * 32;
; #pragma unroll
;     for (int r = 0; r < 16; ++r) {
;         const int qq = crow(r, hi); const float inv = __builtin_amdgcn_rcpf(ol[r]); const int pos = pos0 + qq;
;         const int row = (j == 0) ? MLAT + b * CTXL + pos : b * SEQ + pos - CTXL;
;         GAS bf16* yp = Yp + (size_t)row * DM + r32;
;         yp[0] = (bf16)f2bf(o0[r] * inv); yp[32] = (bf16)f2bf(o1[r] * inv);
;     }
;     asm volatile("s_waitcnt lgkmcnt(0)" ::: "memory");
;     __syncthreads();
.LBB0_150:
	s_setprio 0
	s_lshl_b32 s8, s74, 6
	s_ashr_i32 s9, s8, 31
	v_lshl_add_u64 v[2:3], s[8:9], 1, v[204:205]
	s_lshl_b32 s8, s73, 11
	s_add_i32 s10, s8, 0xffffff00
	s_lshl_b32 s8, s73, 8
	s_add_i32 s11, s8, 0x4000
	s_and_b64 s[8:9], s[44:45], exec
	v_rcp_f32_e32 v0, v48
	s_cselect_b32 s8, s11, s10
	s_add_i32 s8, s8, s7
	v_add_u32_e32 v4, s8, v239
	v_ashrrev_i32_e32 v5, 31, v4
	v_lshlrev_b64 v[6:7], 11, v[4:5]
	v_mul_f32_e32 v5, v32, v0
	v_bfe_u32 v8, v5, 16, 1
	v_lshl_add_u64 v[6:7], v[2:3], 0, v[6:7]
	v_add3_u32 v5, v5, v8, s3
	v_mul_f32_e32 v0, v16, v0
	global_store_short_d16_hi v[6:7], v5, off offset:1280
	v_bfe_u32 v5, v0, 16, 1
	v_add3_u32 v0, v0, v5, s3
	global_store_short_d16_hi v[6:7], v0, off offset:1344
	v_rcp_f32_e32 v0, v49
	v_or_b32_e32 v6, 1, v4
	v_ashrrev_i32_e32 v7, 31, v6
	v_lshlrev_b64 v[6:7], 11, v[6:7]
	v_mul_f32_e32 v5, v33, v0
	v_bfe_u32 v8, v5, 16, 1
	v_lshl_add_u64 v[6:7], v[2:3], 0, v[6:7]
	v_add3_u32 v5, v5, v8, s3
	v_mul_f32_e32 v0, v17, v0
	global_store_short_d16_hi v[6:7], v5, off offset:1280
	v_bfe_u32 v5, v0, 16, 1
	v_add3_u32 v0, v0, v5, s3
	global_store_short_d16_hi v[6:7], v0, off offset:1344
	v_rcp_f32_e32 v0, v50
	v_or_b32_e32 v6, 2, v4
	v_ashrrev_i32_e32 v7, 31, v6
	v_lshlrev_b64 v[6:7], 11, v[6:7]
	v_mul_f32_e32 v5, v34, v0
	v_bfe_u32 v8, v5, 16, 1
	v_lshl_add_u64 v[6:7], v[2:3], 0, v[6:7]
	v_add3_u32 v5, v5, v8, s3
	v_mul_f32_e32 v0, v18, v0
	global_store_short_d16_hi v[6:7], v5, off offset:1280
	v_bfe_u32 v5, v0, 16, 1
	v_add3_u32 v0, v0, v5, s3
	global_store_short_d16_hi v[6:7], v0, off offset:1344
	v_rcp_f32_e32 v0, v51
	v_or_b32_e32 v6, 3, v4
	v_ashrrev_i32_e32 v7, 31, v6
	v_lshlrev_b64 v[6:7], 11, v[6:7]
	v_mul_f32_e32 v5, v35, v0
	v_bfe_u32 v8, v5, 16, 1
	v_lshl_add_u64 v[6:7], v[2:3], 0, v[6:7]
	v_add3_u32 v5, v5, v8, s3
	v_mul_f32_e32 v0, v19, v0
	global_store_short_d16_hi v[6:7], v5, off offset:1280
	v_bfe_u32 v5, v0, 16, 1
	v_add3_u32 v0, v0, v5, s3
	global_store_short_d16_hi v[6:7], v0, off offset:1344
	v_rcp_f32_e32 v0, v52
	v_add_u32_e32 v6, 8, v4
	v_ashrrev_i32_e32 v7, 31, v6
	v_lshlrev_b64 v[6:7], 11, v[6:7]
	v_mul_f32_e32 v5, v36, v0
	v_bfe_u32 v8, v5, 16, 1
	v_lshl_add_u64 v[6:7], v[2:3], 0, v[6:7]
	v_add3_u32 v5, v5, v8, s3
	v_mul_f32_e32 v0, v20, v0
	global_store_short_d16_hi v[6:7], v5, off offset:1280
	v_bfe_u32 v5, v0, 16, 1
	v_add3_u32 v0, v0, v5, s3
	global_store_short_d16_hi v[6:7], v0, off offset:1344
	v_rcp_f32_e32 v0, v53
	v_add_u32_e32 v6, 9, v4
	v_ashrrev_i32_e32 v7, 31, v6
	v_lshlrev_b64 v[6:7], 11, v[6:7]
	v_mul_f32_e32 v5, v37, v0
	v_bfe_u32 v8, v5, 16, 1
	v_lshl_add_u64 v[6:7], v[2:3], 0, v[6:7]
	v_add3_u32 v5, v5, v8, s3
	v_mul_f32_e32 v0, v21, v0
	global_store_short_d16_hi v[6:7], v5, off offset:1280
	v_bfe_u32 v5, v0, 16, 1
	v_add3_u32 v0, v0, v5, s3
	global_store_short_d16_hi v[6:7], v0, off offset:1344
	v_rcp_f32_e32 v0, v54
	v_add_u32_e32 v6, 10, v4
	v_ashrrev_i32_e32 v7, 31, v6
	v_lshlrev_b64 v[6:7], 11, v[6:7]
	v_mul_f32_e32 v5, v38, v0
	v_bfe_u32 v8, v5, 16, 1
	v_lshl_add_u64 v[6:7], v[2:3], 0, v[6:7]
	v_add3_u32 v5, v5, v8, s3
	v_mul_f32_e32 v0, v22, v0
	global_store_short_d16_hi v[6:7], v5, off offset:1280
	v_bfe_u32 v5, v0, 16, 1
	v_add3_u32 v0, v0, v5, s3
	global_store_short_d16_hi v[6:7], v0, off offset:1344
	v_rcp_f32_e32 v0, v55
	v_add_u32_e32 v6, 11, v4
	v_ashrrev_i32_e32 v7, 31, v6
	v_lshlrev_b64 v[6:7], 11, v[6:7]
	v_mul_f32_e32 v5, v39, v0
	v_bfe_u32 v8, v5, 16, 1
	v_lshl_add_u64 v[6:7], v[2:3], 0, v[6:7]
	v_add3_u32 v5, v5, v8, s3
	v_mul_f32_e32 v0, v23, v0
	global_store_short_d16_hi v[6:7], v5, off offset:1280
; #define GAS __attribute__((address_space(1)))
; __device__ __forceinline__ unsigned f2bf(float f) { unsigned u = __builtin_bit_cast(unsigned, f); return (u + 0x7fffu + ((u >> 16) & 1u)) >> 16; }
; __device__ __forceinline__ int crow(int r, int hi) { return (r & 3) + 8 * (r >> 2) + 4 * hi; }
; template <int DK>
; __device__ __forceinline__ void attn_unit(LAS unsigned char* lds, const GAS bf16* Qp, const GAS bf16* Kp, const GAS bf16* Vp, GAS bf16* Yp, int b, int j, int nkeys, int tid, int lane, int wave) {
;     ...
;     const int pos0 = 256 * j + wave * 32;
; #pragma unroll
;     for (int r = 0; r < 16; ++r) {
;         const int qq = crow(r, hi); const float inv = __builtin_amdgcn_rcpf(ol[r]); const int pos = pos0 + qq;
;         const int row = (j == 0) ? MLAT + b * CTXL + pos : b * SEQ + pos - CTXL;
;         GAS bf16* yp = Yp + (size_t)row * DM + r32;
;         yp[0] = (bf16)f2bf(o0[r] * inv); yp[32] = (bf16)f2bf(o1[r] * inv);
;     }
;     asm volatile("s_waitcnt lgkmcnt(0)" ::: "memory");
;     __syncthreads();
	v_bfe_u32 v5, v0, 16, 1
	v_add3_u32 v0, v0, v5, s3
	global_store_short_d16_hi v[6:7], v0, off offset:1344
	v_rcp_f32_e32 v0, v56
	v_add_u32_e32 v6, 16, v4
	v_ashrrev_i32_e32 v7, 31, v6
	v_lshlrev_b64 v[6:7], 11, v[6:7]
	v_mul_f32_e32 v5, v40, v0
	v_bfe_u32 v8, v5, 16, 1
	v_lshl_add_u64 v[6:7], v[2:3], 0, v[6:7]
	v_add3_u32 v5, v5, v8, s3
	v_mul_f32_e32 v0, v24, v0
	global_store_short_d16_hi v[6:7], v5, off offset:1280
	v_bfe_u32 v5, v0, 16, 1
	v_add3_u32 v0, v0, v5, s3
	global_store_short_d16_hi v[6:7], v0, off offset:1344
	v_rcp_f32_e32 v0, v57
	v_add_u32_e32 v6, 17, v4
	v_ashrrev_i32_e32 v7, 31, v6
	v_lshlrev_b64 v[6:7], 11, v[6:7]
	v_mul_f32_e32 v5, v41, v0
	v_bfe_u32 v8, v5, 16, 1
	v_lshl_add_u64 v[6:7], v[2:3], 0, v[6:7]
	v_add3_u32 v5, v5, v8, s3
	v_mul_f32_e32 v0, v25, v0
	global_store_short_d16_hi v[6:7], v5, off offset:1280
	v_bfe_u32 v5, v0, 16, 1
	v_add3_u32 v0, v0, v5, s3
	global_store_short_d16_hi v[6:7], v0, off offset:1344
	v_rcp_f32_e32 v0, v58
	v_add_u32_e32 v6, 18, v4
	v_ashrrev_i32_e32 v7, 31, v6
	v_lshlrev_b64 v[6:7], 11, v[6:7]
	v_mul_f32_e32 v5, v42, v0
	v_bfe_u32 v8, v5, 16, 1
	v_lshl_add_u64 v[6:7], v[2:3], 0, v[6:7]
	v_add3_u32 v5, v5, v8, s3
	v_mul_f32_e32 v0, v26, v0
	global_store_short_d16_hi v[6:7], v5, off offset:1280
	v_bfe_u32 v5, v0, 16, 1
	v_add3_u32 v0, v0, v5, s3
	global_store_short_d16_hi v[6:7], v0, off offset:1344
	v_rcp_f32_e32 v0, v59
	v_add_u32_e32 v6, 19, v4
	v_ashrrev_i32_e32 v7, 31, v6
	v_lshlrev_b64 v[6:7], 11, v[6:7]
	v_mul_f32_e32 v5, v43, v0
	v_bfe_u32 v8, v5, 16, 1
	v_lshl_add_u64 v[6:7], v[2:3], 0, v[6:7]
	v_add3_u32 v5, v5, v8, s3
	v_mul_f32_e32 v0, v27, v0
	global_store_short_d16_hi v[6:7], v5, off offset:1280
	v_bfe_u32 v5, v0, 16, 1
	v_add3_u32 v0, v0, v5, s3
	global_store_short_d16_hi v[6:7], v0, off offset:1344
	v_rcp_f32_e32 v0, v60
	v_add_u32_e32 v6, 24, v4
	v_ashrrev_i32_e32 v7, 31, v6
	v_lshlrev_b64 v[6:7], 11, v[6:7]
	v_mul_f32_e32 v5, v44, v0
	v_bfe_u32 v8, v5, 16, 1
	v_lshl_add_u64 v[6:7], v[2:3], 0, v[6:7]
	v_add3_u32 v5, v5, v8, s3
	v_mul_f32_e32 v0, v28, v0
	global_store_short_d16_hi v[6:7], v5, off offset:1280
	v_bfe_u32 v5, v0, 16, 1
	v_add3_u32 v0, v0, v5, s3
	global_store_short_d16_hi v[6:7], v0, off offset:1344
	v_rcp_f32_e32 v0, v61
	v_add_u32_e32 v6, 25, v4
	v_ashrrev_i32_e32 v7, 31, v6
	v_lshlrev_b64 v[6:7], 11, v[6:7]
	v_mul_f32_e32 v5, v45, v0
	v_bfe_u32 v8, v5, 16, 1
	v_lshl_add_u64 v[6:7], v[2:3], 0, v[6:7]
	v_add3_u32 v5, v5, v8, s3
	v_mul_f32_e32 v0, v29, v0
	global_store_short_d16_hi v[6:7], v5, off offset:1280
	v_bfe_u32 v5, v0, 16, 1
	v_add3_u32 v0, v0, v5, s3
	global_store_short_d16_hi v[6:7], v0, off offset:1344
	v_rcp_f32_e32 v0, v62
	v_add_u32_e32 v6, 26, v4
	v_ashrrev_i32_e32 v7, 31, v6
	v_lshlrev_b64 v[6:7], 11, v[6:7]
	v_mul_f32_e32 v5, v46, v0
	v_bfe_u32 v8, v5, 16, 1
	v_lshl_add_u64 v[6:7], v[2:3], 0, v[6:7]
	v_add3_u32 v5, v5, v8, s3
	v_mul_f32_e32 v0, v30, v0
	global_store_short_d16_hi v[6:7], v5, off offset:1280
	v_bfe_u32 v5, v0, 16, 1
	v_add3_u32 v0, v0, v5, s3
	global_store_short_d16_hi v[6:7], v0, off offset:1344
	v_rcp_f32_e32 v0, v63
	v_add_u32_e32 v4, 27, v4
	v_ashrrev_i32_e32 v5, 31, v4
	v_lshlrev_b64 v[4:5], 11, v[4:5]
	v_lshl_add_u64 v[2:3], v[2:3], 0, v[4:5]
	v_mul_f32_e32 v4, v47, v0
	v_bfe_u32 v5, v4, 16, 1
	v_add3_u32 v4, v4, v5, s3
	v_mul_f32_e32 v0, v31, v0
	global_store_short_d16_hi v[2:3], v4, off offset:1280
	v_bfe_u32 v4, v0, 16, 1
	v_add3_u32 v0, v0, v4, s3
	global_store_short_d16_hi v[2:3], v0, off offset:1344
	s_waitcnt lgkmcnt(0)
	s_barrier
	s_mov_b32 s7, 1
	s_branch .LBB0_167

; #define LAS __attribute__((address_space(3)))
; __device__ __forceinline__ int crow(int r, int hi) { return (r & 3) + 8 * (r >> 2) + 4 * hi; }
; template <int DK>
; __device__ __forceinline__ void attn_unit(LAS unsigned char* lds, const GAS bf16* Qp, const GAS bf16* Kp, const GAS bf16* Vp, GAS bf16* Yp, int b, int j, int nkeys, int tid, int lane, int wave) {
;     ...
;           for (int d0 = 0; d0 < ND; ++d0) {
;               if (d0 + 1 < ND) {
; #pragma unroll
;                   for (int q4 = 0; q4 < 4; ++q4) ka[(d0 + 1) & 1][q4] = *(LAS bf16x8*)(kb + q4 * 32 * KSTR + (d0 + 1) * 32);
;               }
; #pragma unroll
;               for (int q4 = 0; q4 < 4; ++q4) p[q4] = __builtin_amdgcn_mfma_f32_32x32x16_bf16(ka[d0 & 1][q4], qr[d0], d0 == 0 ? negm : p[q4], 0, 0, 0);
;               if (d0 == 0) { if (t + 1 < NT) AT_STORE(cur ^ 1); if (t + 2 < NT) AT_LOAD(t + 2); }
;               __builtin_amdgcn_sched_barrier(0);
;           } }
;         float rma = fmaxf(p[0][0], p[1][0]), rmb = fmaxf(p[2][0], p[3][0]);
; #pragma unroll
;         for (int r = 1; r < 16; ++r) { rma = fmaxf(fmaxf(rma, p[0][r]), p[1][r]); rmb = fmaxf(fmaxf(rmb, p[2][r]), p[3][r]); }
;         float rm = fmaxf(rma, rmb);
;         { const unsigned ru_ = __builtin_bit_cast(unsigned, rm); auto rr_ = __builtin_amdgcn_permlane32_swap(ru_, ru_, false, false);
;           rm = fmaxf(__builtin_bit_cast(float, (unsigned)rr_[0]), __builtin_bit_cast(float, (unsigned)rr_[1])); }
;         if (t == 0 || __any(rm > 8.0f)) {
;             const float dl = (t == 0) ? rm : fmaxf(rm, 0.f), f = __builtin_amdgcn_exp2f(-dl);
;             mhat += dl;
; #pragma unroll
;             for (int r = 0; r < 16; ++r) { p[0][r] -= dl; p[1][r] -= dl; p[2][r] -= dl; p[3][r] -= dl; negm[r] = -mhat; }
;             if (hi == 0) wsf[r32] = f;
;             asm volatile("s_waitcnt lgkmcnt(0)" ::: "memory");
; #pragma unroll
;             for (int r = 0; r < 16; ++r) { const float fr = wsf[crow(r, hi)]; o0[r] *= fr; o1[r] *= fr; ol[r] *= fr; }
;             asm volatile("s_waitcnt lgkmcnt(0)" ::: "memory");
;         }
;         u32x4 pw[8];
;         { LAS unsigned char* vb = lds + cur * AT_VBUF + vfo;
;     ...
;           bf16x8 vfa[2], vfb[2];
;           vfa[0] = AT_VF(0, 0); vfa[1] = AT_VF(1, 0);
;           AT_EXPQ(0);
.LBB0_154:
	s_waitcnt lgkmcnt(7)
	v_mfma_f32_32x32x16_bf16 v[2:17], v[80:83], v[134:137], v[2:17]
	s_waitcnt lgkmcnt(6)
	v_mfma_f32_32x32x16_bf16 v[18:33], v[76:79], v[134:137], v[18:33]
	s_waitcnt lgkmcnt(5)
	v_mfma_f32_32x32x16_bf16 v[34:49], v[72:75], v[134:137], v[34:49]
	ds_read_b128 v[72:75], v242 offset:64
	ds_read_b128 v[76:79], v242 offset:4672
	ds_read_b128 v[80:83], v242 offset:9280
	ds_read_b128 v[84:87], v242 offset:13888
	s_waitcnt lgkmcnt(8)
	v_mfma_f32_32x32x16_bf16 v[52:67], v[68:71], v[134:137], v[52:67]
	s_waitcnt lgkmcnt(3)
	v_mfma_f32_32x32x16_bf16 v[2:17], v[72:75], v[138:141], v[2:17]
	s_waitcnt lgkmcnt(2)
	v_mfma_f32_32x32x16_bf16 v[18:33], v[76:79], v[138:141], v[18:33]
	s_waitcnt lgkmcnt(1)
	v_mfma_f32_32x32x16_bf16 v[34:49], v[80:83], v[138:141], v[34:49]
	ds_read_b128 v[68:71], v242 offset:96
	ds_read_b128 v[72:75], v242 offset:4704
	ds_read_b128 v[76:79], v242 offset:9312
	ds_read_b128 v[80:83], v242 offset:13920
	s_waitcnt lgkmcnt(4)
	v_mfma_f32_32x32x16_bf16 v[52:67], v[84:87], v[138:141], v[52:67]
	s_waitcnt lgkmcnt(3)
	v_mfma_f32_32x32x16_bf16 v[2:17], v[68:71], v[142:145], v[2:17]
	s_waitcnt lgkmcnt(2)
	v_mfma_f32_32x32x16_bf16 v[18:33], v[72:75], v[142:145], v[18:33]
	s_waitcnt lgkmcnt(1)
	v_mfma_f32_32x32x16_bf16 v[34:49], v[76:79], v[142:145], v[34:49]
	s_waitcnt lgkmcnt(0)
	v_mfma_f32_32x32x16_bf16 v[52:67], v[80:83], v[142:145], v[52:67]
	s_nop 11
	v_max_f32_e32 v0, v52, v52
	v_max_f32_e32 v50, v34, v34
	v_max_f32_e32 v0, v50, v0
	v_max3_f32 v50, v2, v18, v3
	v_max3_f32 v0, v0, v35, v53
	v_max3_f32 v50, v50, v19, v4
	v_max3_f32 v0, v0, v36, v54
	v_max3_f32 v50, v50, v20, v5
	v_max3_f32 v0, v0, v37, v55
	v_max3_f32 v50, v50, v21, v6
	v_max3_f32 v0, v0, v38, v56
	v_max3_f32 v50, v50, v22, v7
	v_max3_f32 v0, v0, v39, v57
	v_max3_f32 v50, v50, v23, v8
	v_max3_f32 v0, v0, v40, v58
	v_max3_f32 v50, v50, v24, v9
	v_max3_f32 v0, v0, v41, v59
	v_max3_f32 v50, v50, v25, v10
	v_max3_f32 v0, v0, v42, v60
	v_max3_f32 v50, v50, v26, v11
	v_max3_f32 v0, v0, v43, v61
	v_max3_f32 v50, v50, v27, v12
	v_max3_f32 v0, v0, v44, v62
	v_max3_f32 v50, v50, v28, v13
	v_max3_f32 v0, v0, v45, v63
	v_max3_f32 v50, v50, v29, v14
	v_max3_f32 v0, v0, v46, v64
	v_max3_f32 v50, v50, v30, v15
	v_max3_f32 v0, v0, v47, v65
	v_max3_f32 v50, v50, v31, v16
	v_max3_f32 v0, v0, v48, v66
	v_max3_f32 v50, v50, v32, v17
	v_max3_f32 v0, v0, v49, v67
	v_max3_f32 v0, v50, v33, v0
	v_mov_b32_e32 v50, v0
	s_nop 1
	v_permlane32_swap_b32_e32 v0, v50
	v_max_f32_e32 v50, v50, v50
	v_max_f32_e32 v0, v0, v0
	v_max_f32_e32 v0, v0, v50
	s_and_saveexec_b64 s[22:23], s[40:41]
	v_exp_f32_e64 v50, -v0
	ds_write_b32 v238, v50
	s_or_b64 exec, exec, s[22:23]
	s_waitcnt lgkmcnt(0)
	v_add_u32_e32 v185, s63, v236
	v_sub_f32_e32 v51, v2, v0
	v_sub_f32_e32 v76, v18, v0
	v_sub_f32_e32 v78, v52, v0
	v_sub_f32_e32 v52, v3, v0
	v_sub_f32_e32 v79, v19, v0
	v_sub_f32_e32 v81, v53, v0
	v_sub_f32_e32 v53, v4, v0
	v_sub_f32_e32 v82, v20, v0
	v_sub_f32_e32 v84, v54, v0
	v_sub_f32_e32 v54, v5, v0
	v_sub_f32_e32 v85, v21, v0
	v_sub_f32_e32 v87, v55, v0
	v_sub_f32_e32 v55, v6, v0
	v_sub_f32_e32 v88, v22, v0
	v_sub_f32_e32 v89, v38, v0
	v_sub_f32_e32 v38, v7, v0
	v_sub_f32_e32 v91, v23, v0
	v_sub_f32_e32 v92, v39, v0
	v_sub_f32_e32 v39, v8, v0
	v_sub_f32_e32 v94, v24, v0
	v_sub_f32_e32 v95, v40, v0
	v_sub_f32_e32 v40, v9, v0
	v_sub_f32_e32 v97, v25, v0
	ds_read_b128 v[2:5], v185 offset:64
	ds_read_b128 v[6:9], v185 offset:96
	ds_read_b128 v[18:21], v185
	ds_read_b128 v[22:25], v185 offset:32
	s_waitcnt lgkmcnt(0)
	v_sub_f32_e32 v77, v34, v0
	v_sub_f32_e32 v80, v35, v0
	v_sub_f32_e32 v83, v36, v0
	v_sub_f32_e32 v86, v37, v0
	v_sub_f32_e32 v90, v56, v0
	v_sub_f32_e32 v93, v57, v0
	v_sub_f32_e32 v96, v58, v0
	v_sub_f32_e32 v99, v59, v0
	ds_read_b64_tr_b16 v[34:35], v243 offset:53248
	ds_read_b64_tr_b16 v[36:37], v243 offset:53760
	ds_read_b64_tr_b16 v[56:57], v243 offset:61440
	ds_read_b64_tr_b16 v[58:59], v243 offset:61952
	v_sub_f32_e32 v98, v41, v0
	v_sub_f32_e32 v41, v10, v0
	v_sub_f32_e32 v72, v26, v0
	v_sub_f32_e32 v26, v11, v0
	v_sub_f32_e32 v73, v27, v0
	v_sub_f32_e32 v27, v12, v0
	v_sub_f32_e32 v74, v28, v0
	v_sub_f32_e32 v28, v13, v0
	v_sub_f32_e32 v75, v29, v0
	v_sub_f32_e32 v29, v14, v0
	v_sub_f32_e32 v108, v30, v0
	v_sub_f32_e32 v30, v15, v0
	v_sub_f32_e32 v111, v31, v0
	v_sub_f32_e32 v31, v16, v0
	v_sub_f32_e32 v114, v32, v0
	v_sub_f32_e32 v32, v17, v0
	v_sub_f32_e32 v117, v33, v0
	s_waitcnt lgkmcnt(6)
	v_pk_mul_f32 v[16:17], v[8:9], 0 op_sel_hi:[1,0]
	v_pk_mul_f32 v[12:13], v[4:5], 0 op_sel_hi:[1,0]
	s_waitcnt lgkmcnt(4)
	v_pk_mul_f32 v[8:9], v[24:25], 0 op_sel_hi:[1,0]
	v_pk_mul_f32 v[4:5], v[20:21], 0 op_sel_hi:[1,0]
	v_pk_mul_f32 v[14:15], v[6:7], 0 op_sel_hi:[1,0]
	v_pk_mul_f32 v[10:11], v[2:3], 0 op_sel_hi:[1,0]
	v_pk_mul_f32 v[6:7], v[22:23], 0 op_sel_hi:[1,0]
	v_pk_mul_f32 v[2:3], v[18:19], 0 op_sel_hi:[1,0]
	v_exp_f32_e32 v18, v51
	v_exp_f32_e32 v19, v52
	v_exp_f32_e32 v20, v53
	v_exp_f32_e32 v21, v54
	v_exp_f32_e32 v22, v55
	v_exp_f32_e32 v23, v38
	v_exp_f32_e32 v24, v39
	v_exp_f32_e32 v25, v40
	v_exp_f32_e32 v33, v41
	v_exp_f32_e32 v26, v26
	v_exp_f32_e32 v27, v27
	v_exp_f32_e32 v28, v28
	v_exp_f32_e32 v29, v29
	v_exp_f32_e32 v30, v30
	v_exp_f32_e32 v31, v31
	v_exp_f32_e32 v32, v32
	v_add_f32_e32 v184, 0, v0
	v_xor_b32_e32 v50, 0x80000000, v184
	v_sub_f32_e32 v101, v60, v0
	v_sub_f32_e32 v103, v61, v0
	v_sub_f32_e32 v105, v62, v0
	v_sub_f32_e32 v107, v63, v0
	v_sub_f32_e32 v110, v64, v0
	v_sub_f32_e32 v113, v65, v0
	s_lshr_b32 s4, s4, 7
	v_cvt_pk_bf16_f32 v60, v18, v19
	v_cvt_pk_bf16_f32 v61, v20, v21
	v_cvt_pk_bf16_f32 v62, v22, v23
	v_cvt_pk_bf16_f32 v63, v24, v25
	v_cvt_pk_bf16_f32 v64, v33, v26
	v_cvt_pk_bf16_f32 v65, v27, v28
	v_sub_f32_e32 v100, v42, v0
	v_sub_f32_e32 v102, v43, v0
	v_sub_f32_e32 v104, v44, v0
	v_sub_f32_e32 v106, v45, v0
	v_sub_f32_e32 v109, v46, v0
	v_sub_f32_e32 v112, v47, v0
	v_sub_f32_e32 v115, v48, v0
	v_sub_f32_e32 v116, v66, v0
	v_sub_f32_e32 v118, v49, v0
	v_sub_f32_e32 v0, v67, v0
	v_cvt_pk_bf16_f32 v66, v29, v30
	v_cvt_pk_bf16_f32 v67, v31, v32
	s_waitcnt lgkmcnt(2)
; #define AT_PVK(ks, VF) do { o0 = __builtin_amdgcn_mfma_f32_32x32x16_bf16(__builtin_bit_cast(bf16x8, pw[ks]), VF[0], o0, 0, 0, 0); \
;             o1 = __builtin_amdgcn_mfma_f32_32x32x16_bf16(__builtin_bit_cast(bf16x8, pw[ks]), VF[1], o1, 0, 0, 0); \
;             ol = __builtin_amdgcn_mfma_f32_32x32x16_bf16(__builtin_bit_cast(bf16x8, pw[ks]), ones, ol, 0, 0, 0); } while (0)
; template <int DK>
; __device__ __forceinline__ void attn_unit(LAS unsigned char* lds, const GAS bf16* Qp, const GAS bf16* Kp, const GAS bf16* Vp, GAS bf16* Yp, int b, int j, int nkeys, int tid, int lane, int wave) {
;     ...
;           vfa[0] = AT_VF(0, 0); vfa[1] = AT_VF(1, 0);
;           AT_EXPQ(0);
;           __builtin_amdgcn_sched_barrier(0);
; #pragma unroll
;           for (int q4 = 0; q4 < 4; ++q4) {
;               vfb[0] = AT_VF(0, 2 * q4 + 1); vfb[1] = AT_VF(1, 2 * q4 + 1);
;               AT_PVK(2 * q4, vfa);
;               if (q4 + 1 < 4) { AT_EXPQ(q4 + 1); vfa[0] = AT_VF(0, 2 * q4 + 2); vfa[1] = AT_VF(1, 2 * q4 + 2); }
;               AT_PVK(2 * q4 + 1, vfb);
;               __builtin_amdgcn_sched_barrier(0);
;           }
;     ...
;         }
;         __syncthreads();
	v_mfma_f32_32x32x16_bf16 v[18:33], v[60:63], v[34:37], v[2:17]
	s_mov_b32 s69, s68
	s_mov_b32 s70, s68
	s_mov_b32 s71, s68
	v_mov_b64_e32 v[52:53], s[68:69]
	v_mov_b64_e32 v[54:55], s[70:71]
	ds_read_b64_tr_b16 v[68:69], v243 offset:54272
	ds_read_b64_tr_b16 v[70:71], v243 offset:54784
	v_exp_f32_e32 v51, v72
	s_waitcnt lgkmcnt(2)
	v_mfma_f32_32x32x16_bf16 v[34:49], v[60:63], v[56:59], v[2:17]
	v_exp_f32_e32 v56, v73
	v_exp_f32_e32 v57, v74
	v_exp_f32_e32 v58, v75
	v_exp_f32_e32 v59, v108
	v_exp_f32_e32 v72, v111
	v_exp_f32_e32 v73, v114
	v_cvt_pk_bf16_f32 v57, v57, v58
	v_mfma_f32_32x32x16_bf16 v[2:17], v[60:63], v[52:55], v[2:17]
	v_exp_f32_e32 v60, v117
	v_cvt_pk_bf16_f32 v58, v59, v72
	v_cvt_pk_bf16_f32 v56, v51, v56
	v_exp_f32_e32 v51, v76
	v_cvt_pk_bf16_f32 v59, v73, v60
	ds_read_b64_tr_b16 v[60:61], v243 offset:55296
	ds_read_b64_tr_b16 v[62:63], v243 offset:55808
	v_exp_f32_e32 v76, v79
	s_waitcnt lgkmcnt(2)
	v_mfma_f32_32x32x16_bf16 v[18:33], v[64:67], v[68:71], v[18:33]
	ds_read_b64_tr_b16 v[68:69], v243 offset:62464
	ds_read_b64_tr_b16 v[70:71], v243 offset:62976
	ds_read_b64_tr_b16 v[72:73], v243 offset:63488
	ds_read_b64_tr_b16 v[74:75], v243 offset:64000
	v_exp_f32_e32 v79, v82
	v_exp_f32_e32 v82, v85
	v_exp_f32_e32 v85, v88
	v_exp_f32_e32 v88, v97
	s_waitcnt lgkmcnt(2)
	v_mfma_f32_32x32x16_bf16 v[34:49], v[64:67], v[68:71], v[34:49]
	v_exp_f32_e32 v70, v91
	v_exp_f32_e32 v71, v94
	v_cvt_pk_bf16_f32 v68, v51, v76
	v_cvt_pk_bf16_f32 v69, v79, v82
	v_cvt_pk_bf16_f32 v70, v85, v70
	v_cvt_pk_bf16_f32 v71, v71, v88
	v_mfma_f32_32x32x16_bf16 v[2:17], v[64:67], v[52:55], v[2:17]
	s_nop 0
	v_mfma_f32_32x32x16_bf16 v[18:33], v[68:71], v[60:63], v[18:33]
	ds_read_b64_tr_b16 v[60:61], v243 offset:56320
	ds_read_b64_tr_b16 v[62:63], v243 offset:56832
	v_exp_f32_e32 v65, v104
	v_exp_f32_e32 v66, v106
	v_exp_f32_e32 v67, v109
	v_exp_f32_e32 v51, v100
	v_exp_f32_e32 v64, v102
	v_cvt_pk_bf16_f32 v65, v65, v66
	s_waitcnt lgkmcnt(2)
	v_mfma_f32_32x32x16_bf16 v[34:49], v[68:71], v[72:75], v[34:49]
	v_exp_f32_e32 v72, v112
	v_exp_f32_e32 v73, v115
	v_cvt_pk_bf16_f32 v64, v51, v64
	v_exp_f32_e32 v51, v77
	v_cvt_pk_bf16_f32 v66, v67, v72
	v_exp_f32_e32 v76, v80
	v_exp_f32_e32 v77, v83
	v_mfma_f32_32x32x16_bf16 v[2:17], v[68:71], v[52:55], v[2:17]
	v_exp_f32_e32 v68, v118
	v_exp_f32_e32 v79, v86
	v_exp_f32_e32 v80, v89
	v_exp_f32_e32 v82, v98
	v_cvt_pk_bf16_f32 v67, v73, v68
	ds_read_b64_tr_b16 v[68:69], v243 offset:57344
	ds_read_b64_tr_b16 v[70:71], v243 offset:57856
	s_waitcnt lgkmcnt(2)
	v_mfma_f32_32x32x16_bf16 v[18:33], v[56:59], v[60:63], v[18:33]
	ds_read_b64_tr_b16 v[60:61], v243 offset:64512
	ds_read_b64_tr_b16 v[62:63], v243 offset:65024
	ds_read_b64_tr_b16 v[72:73], v244 offset:12288
	ds_read_b64_tr_b16 v[74:75], v244 offset:12800
	s_waitcnt lgkmcnt(2)
	v_mfma_f32_32x32x16_bf16 v[34:49], v[56:59], v[60:63], v[34:49]
	v_exp_f32_e32 v62, v92
	v_exp_f32_e32 v63, v95
	v_cvt_pk_bf16_f32 v60, v51, v76
	v_cvt_pk_bf16_f32 v61, v77, v79
	v_cvt_pk_bf16_f32 v62, v80, v62
	v_cvt_pk_bf16_f32 v63, v63, v82
	v_mfma_f32_32x32x16_bf16 v[2:17], v[56:59], v[52:55], v[2:17]
	s_nop 0
	v_mfma_f32_32x32x16_bf16 v[18:33], v[60:63], v[68:71], v[18:33]
	ds_read_b64_tr_b16 v[56:57], v243 offset:58368
	ds_read_b64_tr_b16 v[58:59], v243 offset:58880
	v_exp_f32_e32 v51, v101
	v_exp_f32_e32 v68, v103
	v_exp_f32_e32 v69, v105
	v_exp_f32_e32 v70, v107
	v_exp_f32_e32 v71, v110
	v_exp_f32_e32 v0, v0
	s_waitcnt lgkmcnt(2)
	v_mfma_f32_32x32x16_bf16 v[34:49], v[60:63], v[72:75], v[34:49]
	v_exp_f32_e32 v72, v113
	v_exp_f32_e32 v73, v116
	v_exp_f32_e32 v76, v84
	v_exp_f32_e32 v77, v87
	v_exp_f32_e32 v79, v99
	v_mfma_f32_32x32x16_bf16 v[2:17], v[60:63], v[52:55], v[2:17]
	v_cvt_pk_bf16_f32 v60, v51, v68
	v_cvt_pk_bf16_f32 v61, v69, v70
	v_cvt_pk_bf16_f32 v62, v71, v72
	v_cvt_pk_bf16_f32 v63, v73, v0
	ds_read_b64_tr_b16 v[68:69], v243 offset:59392
	ds_read_b64_tr_b16 v[70:71], v243 offset:59904
	v_exp_f32_e32 v0, v78
	v_exp_f32_e32 v51, v81
	s_waitcnt lgkmcnt(2)
	v_mfma_f32_32x32x16_bf16 v[18:33], v[64:67], v[56:59], v[18:33]
	ds_read_b64_tr_b16 v[56:57], v244 offset:13312
	ds_read_b64_tr_b16 v[58:59], v244 offset:13824
	ds_read_b64_tr_b16 v[72:73], v244 offset:14336
	ds_read_b64_tr_b16 v[74:75], v244 offset:14848
	v_exp_f32_e32 v78, v90
	s_waitcnt lgkmcnt(2)
	v_mfma_f32_32x32x16_bf16 v[34:49], v[64:67], v[56:59], v[34:49]
	v_exp_f32_e32 v58, v93
	v_exp_f32_e32 v59, v96
	v_cvt_pk_bf16_f32 v56, v0, v51
	v_cvt_pk_bf16_f32 v57, v76, v77
	v_cvt_pk_bf16_f32 v58, v78, v58
	v_cvt_pk_bf16_f32 v59, v59, v79
	v_mfma_f32_32x32x16_bf16 v[2:17], v[64:67], v[52:55], v[2:17]
	s_nop 0
	v_mfma_f32_32x32x16_bf16 v[18:33], v[56:59], v[68:71], v[18:33]
	s_waitcnt lgkmcnt(0)
	v_mfma_f32_32x32x16_bf16 v[34:49], v[56:59], v[72:75], v[34:49]
	v_mfma_f32_32x32x16_bf16 v[2:17], v[56:59], v[52:55], v[2:17]
	ds_read_b64_tr_b16 v[56:57], v243 offset:60416
	ds_read_b64_tr_b16 v[58:59], v243 offset:60928
	ds_read_b64_tr_b16 v[64:65], v244 offset:15360
	ds_read_b64_tr_b16 v[66:67], v244 offset:15872
	s_waitcnt lgkmcnt(2)
	v_mfma_f32_32x32x16_bf16 v[18:33], v[60:63], v[56:59], v[18:33]
	s_waitcnt lgkmcnt(0)
	v_mfma_f32_32x32x16_bf16 v[34:49], v[60:63], v[64:67], v[34:49]
	v_mfma_f32_32x32x16_bf16 v[2:17], v[60:63], v[52:55], v[2:17]
	v_mad_i64_i32 v[180:181], s[8:9], s6, v213, v[208:209]
	v_mad_i64_i32 v[182:183], s[6:7], s6, v213, v[210:211]
	s_lshl_b32 s6, s4, 14
	s_add_u32 s6, s6, 0xffffc000
	s_mov_b64 s[22:23], 0
	s_mov_b32 s7, 3
	v_mov_b32_e32 v51, v50
	v_mov_b32_e32 v52, v50
	v_mov_b32_e32 v53, v50
	v_mov_b32_e32 v54, v50
	v_mov_b32_e32 v55, v50
	v_mov_b32_e32 v56, v50
	v_mov_b32_e32 v57, v50
	v_mov_b32_e32 v58, v50
	v_mov_b32_e32 v59, v50
	v_mov_b32_e32 v60, v50
	v_mov_b32_e32 v61, v50
	v_mov_b32_e32 v62, v50
	v_mov_b32_e32 v63, v50
	v_mov_b32_e32 v64, v50
	v_mov_b32_e32 v65, v50
	s_barrier
	s_cmp_lt_u32 s97, 4
	s_cbranch_scc1 .Lprio_2
	s_setprio 1
; __device__ __forceinline__ int crow(int r, int hi) { return (r & 3) + 8 * (r >> 2) + 4 * hi; }
; template <int DK>
; __device__ __forceinline__ void attn_unit(LAS unsigned char* lds, const GAS bf16* Qp, const GAS bf16* Kp, const GAS bf16* Vp, GAS bf16* Yp, int b, int j, int nkeys, int tid, int lane, int wave) {
;     ...
;         if (t == 0 || __any(rm > 8.0f)) {
;             const float dl = (t == 0) ? rm : fmaxf(rm, 0.f), f = __builtin_amdgcn_exp2f(-dl);
;             mhat += dl;
; #pragma unroll
;             for (int r = 0; r < 16; ++r) { p[0][r] -= dl; p[1][r] -= dl; p[2][r] -= dl; p[3][r] -= dl; negm[r] = -mhat; }
;             if (hi == 0) wsf[r32] = f;
;             asm volatile("s_waitcnt lgkmcnt(0)" ::: "memory");
; #pragma unroll
;             for (int r = 0; r < 16; ++r) { const float fr = wsf[crow(r, hi)]; o0[r] *= fr; o1[r] *= fr; ol[r] *= fr; }
;             asm volatile("s_waitcnt lgkmcnt(0)" ::: "memory");
;         }
.Lprio_2:
	s_branch .LBB0_159
.LBB0_157:
	s_or_b64 exec, exec, s[46:47]
	s_waitcnt lgkmcnt(0)
	ds_read_b128 v[50:53], v185
	ds_read_b128 v[54:57], v185 offset:32
	ds_read_b128 v[58:61], v185 offset:64
	ds_read_b128 v[162:165], v185 offset:96
	v_add_f32_e32 v184, v184, v0
	s_waitcnt lgkmcnt(0)
	v_xor_b32_e32 v65, 0x80000000, v184
	v_pk_add_f32 v[114:115], v[114:115], v[0:1] op_sel_hi:[1,0] neg_lo:[0,1] neg_hi:[0,1]
	v_pk_add_f32 v[98:99], v[98:99], v[0:1] op_sel_hi:[1,0] neg_lo:[0,1] neg_hi:[0,1]
	v_pk_add_f32 v[82:83], v[82:83], v[0:1] op_sel_hi:[1,0] neg_lo:[0,1] neg_hi:[0,1]
	v_pk_add_f32 v[66:67], v[66:67], v[0:1] op_sel_hi:[1,0] neg_lo:[0,1] neg_hi:[0,1]
	v_pk_add_f32 v[116:117], v[116:117], v[0:1] op_sel_hi:[1,0] neg_lo:[0,1] neg_hi:[0,1]
	v_pk_add_f32 v[100:101], v[100:101], v[0:1] op_sel_hi:[1,0] neg_lo:[0,1] neg_hi:[0,1]
	v_pk_add_f32 v[84:85], v[84:85], v[0:1] op_sel_hi:[1,0] neg_lo:[0,1] neg_hi:[0,1]
	v_pk_add_f32 v[68:69], v[68:69], v[0:1] op_sel_hi:[1,0] neg_lo:[0,1] neg_hi:[0,1]
	v_pk_add_f32 v[118:119], v[118:119], v[0:1] op_sel_hi:[1,0] neg_lo:[0,1] neg_hi:[0,1]
	v_pk_add_f32 v[102:103], v[102:103], v[0:1] op_sel_hi:[1,0] neg_lo:[0,1] neg_hi:[0,1]
	v_pk_add_f32 v[86:87], v[86:87], v[0:1] op_sel_hi:[1,0] neg_lo:[0,1] neg_hi:[0,1]
	v_pk_add_f32 v[70:71], v[70:71], v[0:1] op_sel_hi:[1,0] neg_lo:[0,1] neg_hi:[0,1]
	v_pk_add_f32 v[120:121], v[120:121], v[0:1] op_sel_hi:[1,0] neg_lo:[0,1] neg_hi:[0,1]
	v_pk_add_f32 v[104:105], v[104:105], v[0:1] op_sel_hi:[1,0] neg_lo:[0,1] neg_hi:[0,1]
	v_pk_add_f32 v[88:89], v[88:89], v[0:1] op_sel_hi:[1,0] neg_lo:[0,1] neg_hi:[0,1]
	v_pk_add_f32 v[72:73], v[72:73], v[0:1] op_sel_hi:[1,0] neg_lo:[0,1] neg_hi:[0,1]
	v_pk_add_f32 v[122:123], v[122:123], v[0:1] op_sel_hi:[1,0] neg_lo:[0,1] neg_hi:[0,1]
	v_pk_add_f32 v[106:107], v[106:107], v[0:1] op_sel_hi:[1,0] neg_lo:[0,1] neg_hi:[0,1]
	v_pk_add_f32 v[90:91], v[90:91], v[0:1] op_sel_hi:[1,0] neg_lo:[0,1] neg_hi:[0,1]
	v_pk_add_f32 v[74:75], v[74:75], v[0:1] op_sel_hi:[1,0] neg_lo:[0,1] neg_hi:[0,1]
	v_pk_add_f32 v[124:125], v[124:125], v[0:1] op_sel_hi:[1,0] neg_lo:[0,1] neg_hi:[0,1]
	v_pk_add_f32 v[108:109], v[108:109], v[0:1] op_sel_hi:[1,0] neg_lo:[0,1] neg_hi:[0,1]
	v_pk_add_f32 v[92:93], v[92:93], v[0:1] op_sel_hi:[1,0] neg_lo:[0,1] neg_hi:[0,1]
	v_pk_add_f32 v[76:77], v[76:77], v[0:1] op_sel_hi:[1,0] neg_lo:[0,1] neg_hi:[0,1]
	v_pk_add_f32 v[126:127], v[126:127], v[0:1] op_sel_hi:[1,0] neg_lo:[0,1] neg_hi:[0,1]
	v_pk_add_f32 v[110:111], v[110:111], v[0:1] op_sel_hi:[1,0] neg_lo:[0,1] neg_hi:[0,1]
	v_pk_add_f32 v[94:95], v[94:95], v[0:1] op_sel_hi:[1,0] neg_lo:[0,1] neg_hi:[0,1]
	v_pk_add_f32 v[78:79], v[78:79], v[0:1] op_sel_hi:[1,0] neg_lo:[0,1] neg_hi:[0,1]
	v_pk_add_f32 v[128:129], v[128:129], v[0:1] op_sel_hi:[1,0] neg_lo:[0,1] neg_hi:[0,1]
	v_pk_add_f32 v[112:113], v[112:113], v[0:1] op_sel_hi:[1,0] neg_lo:[0,1] neg_hi:[0,1]
	v_pk_add_f32 v[96:97], v[96:97], v[0:1] op_sel_hi:[1,0] neg_lo:[0,1] neg_hi:[0,1]
	v_pk_add_f32 v[80:81], v[80:81], v[0:1] op_sel_hi:[1,0] neg_lo:[0,1] neg_hi:[0,1]
	s_waitcnt lgkmcnt(0)
	v_pk_mul_f32 v[30:31], v[30:31], v[162:163]
	v_pk_mul_f32 v[26:27], v[26:27], v[58:59]
	v_pk_mul_f32 v[22:23], v[22:23], v[54:55]
	v_pk_mul_f32 v[32:33], v[32:33], v[164:165]
	v_pk_mul_f32 v[28:29], v[28:29], v[60:61]
	v_pk_mul_f32 v[24:25], v[24:25], v[56:57]
	v_pk_mul_f32 v[20:21], v[20:21], v[52:53]
	v_pk_mul_f32 v[18:19], v[18:19], v[50:51]
	v_pk_mul_f32 v[46:47], v[46:47], v[162:163]
	v_pk_mul_f32 v[42:43], v[42:43], v[58:59]
	v_pk_mul_f32 v[38:39], v[38:39], v[54:55]
	v_pk_mul_f32 v[48:49], v[48:49], v[164:165]
	v_pk_mul_f32 v[44:45], v[44:45], v[60:61]
	v_pk_mul_f32 v[40:41], v[40:41], v[56:57]
	v_pk_mul_f32 v[36:37], v[36:37], v[52:53]
	v_pk_mul_f32 v[34:35], v[34:35], v[50:51]
	v_pk_mul_f32 v[14:15], v[14:15], v[162:163]
	v_pk_mul_f32 v[10:11], v[10:11], v[58:59]
	v_pk_mul_f32 v[6:7], v[6:7], v[54:55]
	v_pk_mul_f32 v[16:17], v[16:17], v[164:165]
	v_pk_mul_f32 v[12:13], v[12:13], v[60:61]
	v_pk_mul_f32 v[8:9], v[8:9], v[56:57]
	v_pk_mul_f32 v[4:5], v[4:5], v[52:53]
	v_pk_mul_f32 v[2:3], v[2:3], v[50:51]
	v_mov_b32_e32 v64, v65
	v_mov_b32_e32 v63, v65
	v_mov_b32_e32 v62, v65
	v_mov_b32_e32 v61, v65
	v_mov_b32_e32 v60, v65
	v_mov_b32_e32 v59, v65
	v_mov_b32_e32 v58, v65
	v_mov_b32_e32 v57, v65
	v_mov_b32_e32 v56, v65
	v_mov_b32_e32 v55, v65
	v_mov_b32_e32 v54, v65
	v_mov_b32_e32 v53, v65
	v_mov_b32_e32 v52, v65
	v_mov_b32_e32 v51, v65
	v_mov_b32_e32 v50, v65

; #define GAS __attribute__((address_space(1)))
; __device__ __forceinline__ unsigned f2bf(float f) { unsigned u = __builtin_bit_cast(unsigned, f); return (u + 0x7fffu + ((u >> 16) & 1u)) >> 16; }
; __device__ __forceinline__ int crow(int r, int hi) { return (r & 3) + 8 * (r >> 2) + 4 * hi; }
; template <int DK>
; __device__ __forceinline__ void attn_unit(LAS unsigned char* lds, const GAS bf16* Qp, const GAS bf16* Kp, const GAS bf16* Vp, GAS bf16* Yp, int b, int j, int nkeys, int tid, int lane, int wave) {
;     ...
;     const int pos0 = 256 * j + wave * 32;
; #pragma unroll
;     for (int r = 0; r < 16; ++r) {
;         const int qq = crow(r, hi); const float inv = __builtin_amdgcn_rcpf(ol[r]); const int pos = pos0 + qq;
;         const int row = (j == 0) ? MLAT + b * CTXL + pos : b * SEQ + pos - CTXL;
;         GAS bf16* yp = Yp + (size_t)row * DM + r32;
;         yp[0] = (bf16)f2bf(o0[r] * inv); yp[32] = (bf16)f2bf(o1[r] * inv);
;     }
;     asm volatile("s_waitcnt lgkmcnt(0)" ::: "memory");
;     __syncthreads();
.LBB0_166:
	s_setprio 0
	s_lshl_b32 s6, s74, 6
	s_ashr_i32 s7, s6, 31
	v_lshl_add_u64 v[50:51], s[6:7], 1, v[204:205]
	s_lshl_b32 s4, s73, 11
	s_lshl_b32 s6, s73, 8
	s_addk_i32 s4, 0xff00
	s_add_i32 s8, s6, 0x4000
	v_rcp_f32_e32 v0, v2
	s_and_b64 s[6:7], s[44:45], exec
	s_cselect_b32 s4, s8, s4
	s_add_i32 s4, s4, s5
	v_add_u32_e32 v52, s4, v239
	v_ashrrev_i32_e32 v53, 31, v52
	v_mul_f32_e32 v2, v18, v0
	v_lshlrev_b64 v[54:55], 11, v[52:53]
	v_bfe_u32 v18, v2, 16, 1
	v_lshl_add_u64 v[54:55], v[50:51], 0, v[54:55]
	v_add3_u32 v2, v2, v18, s3
	v_mul_f32_e32 v0, v34, v0
	global_store_short_d16_hi v[54:55], v2, off
	v_bfe_u32 v2, v0, 16, 1
	v_add3_u32 v0, v0, v2, s3
	global_store_short_d16_hi v[54:55], v0, off offset:64
	v_rcp_f32_e32 v0, v3
	v_or_b32_e32 v2, 1, v52
	v_ashrrev_i32_e32 v3, 31, v2
	v_lshlrev_b64 v[2:3], 11, v[2:3]
	v_mul_f32_e32 v18, v19, v0
	v_bfe_u32 v19, v18, 16, 1
	v_lshl_add_u64 v[2:3], v[50:51], 0, v[2:3]
	v_add3_u32 v18, v18, v19, s3
	v_mul_f32_e32 v0, v35, v0
	global_store_short_d16_hi v[2:3], v18, off
	v_bfe_u32 v18, v0, 16, 1
	v_add3_u32 v0, v0, v18, s3
	global_store_short_d16_hi v[2:3], v0, off offset:64
	v_rcp_f32_e32 v0, v4
	v_or_b32_e32 v2, 2, v52
	v_ashrrev_i32_e32 v3, 31, v2
	v_lshlrev_b64 v[2:3], 11, v[2:3]
	v_mul_f32_e32 v4, v20, v0
	v_bfe_u32 v18, v4, 16, 1
	v_lshl_add_u64 v[2:3], v[50:51], 0, v[2:3]
	v_add3_u32 v4, v4, v18, s3
	v_mul_f32_e32 v0, v36, v0
	global_store_short_d16_hi v[2:3], v4, off
	v_bfe_u32 v4, v0, 16, 1
	v_add3_u32 v0, v0, v4, s3
	global_store_short_d16_hi v[2:3], v0, off offset:64
	v_rcp_f32_e32 v0, v5
	v_or_b32_e32 v2, 3, v52
	v_ashrrev_i32_e32 v3, 31, v2
	v_lshlrev_b64 v[2:3], 11, v[2:3]
	v_mul_f32_e32 v4, v21, v0
	v_bfe_u32 v5, v4, 16, 1
	v_lshl_add_u64 v[2:3], v[50:51], 0, v[2:3]
	v_add3_u32 v4, v4, v5, s3
	v_mul_f32_e32 v0, v37, v0
	global_store_short_d16_hi v[2:3], v4, off
	v_bfe_u32 v4, v0, 16, 1
	v_add3_u32 v0, v0, v4, s3
	global_store_short_d16_hi v[2:3], v0, off offset:64
	v_rcp_f32_e32 v0, v6
	v_add_u32_e32 v2, 8, v52
	v_ashrrev_i32_e32 v3, 31, v2
	v_lshlrev_b64 v[2:3], 11, v[2:3]
	v_mul_f32_e32 v4, v22, v0
	v_bfe_u32 v5, v4, 16, 1
	v_lshl_add_u64 v[2:3], v[50:51], 0, v[2:3]
	v_add3_u32 v4, v4, v5, s3
	v_mul_f32_e32 v0, v38, v0
	global_store_short_d16_hi v[2:3], v4, off
	v_bfe_u32 v4, v0, 16, 1
	v_add3_u32 v0, v0, v4, s3
	global_store_short_d16_hi v[2:3], v0, off offset:64
	v_rcp_f32_e32 v0, v7
	v_add_u32_e32 v2, 9, v52
	v_ashrrev_i32_e32 v3, 31, v2
	v_lshlrev_b64 v[2:3], 11, v[2:3]
	v_mul_f32_e32 v4, v23, v0
	v_bfe_u32 v5, v4, 16, 1
	v_lshl_add_u64 v[2:3], v[50:51], 0, v[2:3]
	v_add3_u32 v4, v4, v5, s3
	v_mul_f32_e32 v0, v39, v0
	global_store_short_d16_hi v[2:3], v4, off
	v_bfe_u32 v4, v0, 16, 1
	v_add3_u32 v0, v0, v4, s3
	global_store_short_d16_hi v[2:3], v0, off offset:64
	v_rcp_f32_e32 v0, v8
	v_add_u32_e32 v2, 10, v52
	v_ashrrev_i32_e32 v3, 31, v2
	v_lshlrev_b64 v[2:3], 11, v[2:3]
	v_mul_f32_e32 v4, v24, v0
	v_bfe_u32 v5, v4, 16, 1
	v_lshl_add_u64 v[2:3], v[50:51], 0, v[2:3]
	v_add3_u32 v4, v4, v5, s3
	v_mul_f32_e32 v0, v40, v0
	global_store_short_d16_hi v[2:3], v4, off
	v_bfe_u32 v4, v0, 16, 1
	v_add3_u32 v0, v0, v4, s3
	global_store_short_d16_hi v[2:3], v0, off offset:64
	v_rcp_f32_e32 v0, v9
	v_add_u32_e32 v2, 11, v52
	v_ashrrev_i32_e32 v3, 31, v2
	v_lshlrev_b64 v[2:3], 11, v[2:3]
	v_mul_f32_e32 v4, v25, v0
	v_bfe_u32 v5, v4, 16, 1
	v_lshl_add_u64 v[2:3], v[50:51], 0, v[2:3]
	v_add3_u32 v4, v4, v5, s3
	v_mul_f32_e32 v0, v41, v0
	global_store_short_d16_hi v[2:3], v4, off
	v_bfe_u32 v4, v0, 16, 1
	v_add3_u32 v0, v0, v4, s3
	global_store_short_d16_hi v[2:3], v0, off offset:64
	v_rcp_f32_e32 v0, v10
	v_add_u32_e32 v2, 16, v52
	v_ashrrev_i32_e32 v3, 31, v2
	v_lshlrev_b64 v[2:3], 11, v[2:3]
	v_mul_f32_e32 v4, v26, v0
	v_bfe_u32 v5, v4, 16, 1
	v_lshl_add_u64 v[2:3], v[50:51], 0, v[2:3]
	v_add3_u32 v4, v4, v5, s3
	v_mul_f32_e32 v0, v42, v0
	global_store_short_d16_hi v[2:3], v4, off
	v_bfe_u32 v4, v0, 16, 1
	v_add3_u32 v0, v0, v4, s3
	global_store_short_d16_hi v[2:3], v0, off offset:64
	v_rcp_f32_e32 v0, v11
	v_add_u32_e32 v2, 17, v52
	v_ashrrev_i32_e32 v3, 31, v2
	v_lshlrev_b64 v[2:3], 11, v[2:3]
	v_mul_f32_e32 v4, v27, v0
	v_bfe_u32 v5, v4, 16, 1
	v_lshl_add_u64 v[2:3], v[50:51], 0, v[2:3]
	v_add3_u32 v4, v4, v5, s3
	v_mul_f32_e32 v0, v43, v0
	global_store_short_d16_hi v[2:3], v4, off
	v_bfe_u32 v4, v0, 16, 1
	v_add3_u32 v0, v0, v4, s3
	global_store_short_d16_hi v[2:3], v0, off offset:64
	v_rcp_f32_e32 v0, v12
	v_add_u32_e32 v2, 18, v52
	v_ashrrev_i32_e32 v3, 31, v2
	v_lshlrev_b64 v[2:3], 11, v[2:3]
	v_mul_f32_e32 v4, v28, v0
	v_bfe_u32 v5, v4, 16, 1
	v_lshl_add_u64 v[2:3], v[50:51], 0, v[2:3]
	v_add3_u32 v4, v4, v5, s3
	v_mul_f32_e32 v0, v44, v0
	global_store_short_d16_hi v[2:3], v4, off
	v_bfe_u32 v4, v0, 16, 1
	v_add3_u32 v0, v0, v4, s3
	global_store_short_d16_hi v[2:3], v0, off offset:64
	v_rcp_f32_e32 v0, v13
	v_add_u32_e32 v2, 19, v52
	v_ashrrev_i32_e32 v3, 31, v2
	v_lshlrev_b64 v[2:3], 11, v[2:3]
	v_mul_f32_e32 v4, v29, v0
	v_bfe_u32 v5, v4, 16, 1
	v_lshl_add_u64 v[2:3], v[50:51], 0, v[2:3]
	v_add3_u32 v4, v4, v5, s3
	v_mul_f32_e32 v0, v45, v0
	global_store_short_d16_hi v[2:3], v4, off
	v_bfe_u32 v4, v0, 16, 1
	v_add3_u32 v0, v0, v4, s3
	global_store_short_d16_hi v[2:3], v0, off offset:64
	v_rcp_f32_e32 v0, v14
	v_add_u32_e32 v2, 24, v52
	v_ashrrev_i32_e32 v3, 31, v2
	v_lshlrev_b64 v[2:3], 11, v[2:3]
	v_mul_f32_e32 v4, v30, v0
	v_bfe_u32 v5, v4, 16, 1
	v_lshl_add_u64 v[2:3], v[50:51], 0, v[2:3]
	v_add3_u32 v4, v4, v5, s3
	v_mul_f32_e32 v0, v46, v0
	global_store_short_d16_hi v[2:3], v4, off
	v_bfe_u32 v4, v0, 16, 1
	v_add3_u32 v0, v0, v4, s3
	global_store_short_d16_hi v[2:3], v0, off offset:64
	v_rcp_f32_e32 v0, v15
	v_add_u32_e32 v2, 25, v52
	v_ashrrev_i32_e32 v3, 31, v2
	v_lshlrev_b64 v[2:3], 11, v[2:3]
	v_mul_f32_e32 v4, v31, v0
	v_bfe_u32 v5, v4, 16, 1
	v_lshl_add_u64 v[2:3], v[50:51], 0, v[2:3]
	v_add3_u32 v4, v4, v5, s3
	v_mul_f32_e32 v0, v47, v0
	global_store_short_d16_hi v[2:3], v4, off
	v_bfe_u32 v4, v0, 16, 1
	v_add3_u32 v0, v0, v4, s3
	global_store_short_d16_hi v[2:3], v0, off offset:64
	v_rcp_f32_e32 v0, v16
	v_add_u32_e32 v2, 26, v52
	v_ashrrev_i32_e32 v3, 31, v2
	v_lshlrev_b64 v[2:3], 11, v[2:3]
	v_mul_f32_e32 v4, v32, v0
	v_bfe_u32 v5, v4, 16, 1
	v_lshl_add_u64 v[2:3], v[50:51], 0, v[2:3]
	v_add3_u32 v4, v4, v5, s3
	v_mul_f32_e32 v0, v48, v0
	global_store_short_d16_hi v[2:3], v4, off
	v_bfe_u32 v4, v0, 16, 1
	v_add3_u32 v0, v0, v4, s3
	global_store_short_d16_hi v[2:3], v0, off offset:64
	v_rcp_f32_e32 v0, v17
	v_add_u32_e32 v2, 27, v52
	v_ashrrev_i32_e32 v3, 31, v2
	v_lshlrev_b64 v[2:3], 11, v[2:3]
	v_mul_f32_e32 v4, v33, v0
	v_bfe_u32 v5, v4, 16, 1
	v_lshl_add_u64 v[2:3], v[50:51], 0, v[2:3]
	v_add3_u32 v4, v4, v5, s3
	v_mul_f32_e32 v0, v49, v0
	global_store_short_d16_hi v[2:3], v4, off
	v_bfe_u32 v4, v0, 16, 1
	v_add3_u32 v0, v0, v4, s3
	global_store_short_d16_hi v[2:3], v0, off offset:64
	s_waitcnt lgkmcnt(0)
	s_mov_b32 s7, 0
	s_barrier
